# lean7 = lean6 + FFN-up epilogue row statistics prefetched one tile ahead into spare VGPRs (no vmcnt drain in that epilogue)
# baseline (speedup 1.0000x reference)
; #define PG8_STAGE(bufoff, gbase, voff) do { _Pragma("unroll") for (int _i = 0; _i < 2; ++_i) \
;         __builtin_amdgcn_global_load_lds((const unsigned*)((const char*)(gbase) + (voff)[_i]), (PG8_LAS unsigned*)(lds + (bufoff) + ldsw + _i * 8192), 16, 0, 0); } while (0)
; #define PG8_LDA(dst, b, h) do { _Pragma("unroll") for (int m = 0; m < 4; ++m) _Pragma("unroll") for (int k = 0; k < 2; ++k) dst[m][k] = *(const PG8_LAS bf16x8*)(lds + PG8_SA(b, h) + aoff + m * 2048 + k * 1024); } while (0)
; #define PG8_LDB(dst, b, h) do { _Pragma("unroll") for (int n = 0; n < 2; ++n) _Pragma("unroll") for (int k = 0; k < 2; ++k) dst[n][k] = *(const PG8_LAS bf16x8*)(lds + PG8_SB(b, h) + boff + n * 2048 + k * 1024); } while (0)
; #define PG8_WAIT_V(n) asm volatile("s_waitcnt vmcnt(" #n ")" ::: "memory")
; #define PG8_WAIT_L(n) asm volatile("s_waitcnt lgkmcnt(" #n ")" ::: "memory")
; #define PG8_BAR __builtin_amdgcn_s_barrier()
; #define PG8_SCHED __builtin_amdgcn_sched_barrier(0)
; template <class Epi, class Sched, bool ALIGN_EPI = false, bool SP2 = false>
; __device__ __forceinline__ void gemm_phase(PG8_LAS unsigned char* lds, const Gemm g, const Sched& S, const Epi& E) {
;     ...
;         const bool has_next = S.next(ui + 1, nxt);
;         const char* nA = has_next ? (const char*)g.A + (size_t)nxt.pm * tstep : cA; const char* nB = has_next ? (const char*)g.Bt + (size_t)nxt.pn * tstep : cB;
;         for (int t = 0; t < nt; t += 2) {
;             const bool last = (t == nt - 2);
;             const char* a1 = cA + (size_t)(t + 1) * kstep;
;             const char* a2 = last ? nA : cA + (size_t)(t + 2) * kstep; const char* b2 = last ? nB : cB + (size_t)(t + 2) * kstep;
;             const char* a3 = a2 + kstep; const char* b3 = b2 + kstep;
;             if (last && has_next) S.a_ready(nxt);
;             if constexpr (SP2) {
;             PG8_LDB(B0, 0, 0); PG8_LDB(B1, 0, 1); PG8_SCHED; PG8_LDA(At, 0, 0); PG8_STAGE(PG8_SA(1, 1), a1 + hstep, voffA);
;             PG8_WAIT_V(8); PG8_WAIT_L(0); PG8_BAR; PG8_MMA(0, 0, At, B0); PG8_MMA(0, 1, At, B1); PG8_BAR; PG8_SCHED;
;             PG8_LDA(At, 0, 1); PG8_STAGE(PG8_SB(0, 0), b2, voffB); PG8_STAGE(PG8_SB(0, 1), b2 + hstep, voffB); PG8_STAGE(PG8_SA(0, 0), a2, voffA);
;             PG8_WAIT_V(8); PG8_WAIT_L(0); PG8_BAR; PG8_MMA(1, 0, At, B0); PG8_MMA(1, 1, At, B1); PG8_BAR; PG8_SCHED;
.LBB0_1355:
	s_ashr_i32 s11, s10, 31
	s_lshl_b64 s[12:13], s[10:11], 19
	s_add_u32 s12, s22, s12
	s_addc_u32 s13, s23, s13
	s_and_b64 s[14:15], s[2:3], exec
	s_cselect_b32 s11, s13, s19
	s_cselect_b32 s40, s12, s18
	s_ashr_i32 s9, s8, 31
	s_lshl_b64 s[14:15], s[8:9], 19
	s_add_u32 s14, s27, s14
	s_addc_u32 s15, s28, s15
	s_and_b64 s[62:63], s[2:3], exec
	s_cselect_b32 s9, s15, s21
	s_cselect_b32 s61, s14, s20
	s_add_u32 s18, s18, 0xc000
	s_addc_u32 s19, s19, 0
	s_add_u32 s66, s20, 0x10000
	v_mov_b32_e32 v0, 0
	s_addc_u32 s67, s21, 0
	s_mov_b32 s68, -2
	v_add_u32_e32 v254, 0x10000, v162
	s_add_u32 s20, s18, 0x4000
	s_addc_u32 s21, s19, 0
	s_cmp_eq_u32 s68, 12
	s_cselect_b32 s64, s40, s20
	s_cselect_b32 s65, s11, s21
	s_cselect_b32 s62, s61, s66
	s_cselect_b32 s63, s9, s67
	ds_read_b128 v[128:131], v254
	ds_read_b128 v[132:135], v254 offset:1024
	ds_read_b128 v[136:139], v254 offset:2048
	ds_read_b128 v[140:143], v254 offset:3072
	ds_read_b128 v[156:159], v254 offset:16384
	ds_read_b128 v[164:167], v254 offset:17408
	ds_read_b128 v[168:171], v254 offset:18432
	ds_read_b128 v[172:175], v254 offset:19456
	s_add_i32 m0, s37, 0xc000
	ds_read_b128 v[176:179], v163
	ds_read_b128 v[180:183], v163 offset:1024
	ds_read_b128 v[184:187], v163 offset:2048
	ds_read_b128 v[188:191], v163 offset:3072
	ds_read_b128 v[192:195], v163 offset:4096
	ds_read_b128 v[196:199], v163 offset:5120
	ds_read_b128 v[200:203], v163 offset:6144
	ds_read_b128 v[204:207], v163 offset:7168
	global_load_lds_dwordx4 v152, s[18:19]
	s_add_i32 m0, s37, 0xe000
	s_add_u32 s20, s64, 0x8000
	s_addc_u32 s21, s65, 0
	global_load_lds_dwordx4 v154, s[18:19]
	s_waitcnt vmcnt(8) lgkmcnt(0)
	s_barrier
	v_mfma_f32_16x16x32_bf16 v[124:127], v[128:131], v[176:179], 0
	v_mfma_f32_16x16x32_bf16 v[120:123], v[136:139], v[176:179], 0
	v_mfma_f32_16x16x32_bf16 v[108:111], v[128:131], v[184:187], 0
	v_mfma_f32_16x16x32_bf16 v[104:107], v[136:139], v[184:187], 0
	v_mfma_f32_16x16x32_bf16 v[92:95], v[128:131], v[192:195], 0
	v_mfma_f32_16x16x32_bf16 v[88:91], v[136:139], v[192:195], 0
	v_mfma_f32_16x16x32_bf16 v[76:79], v[128:131], v[200:203], 0
	v_mfma_f32_16x16x32_bf16 v[72:75], v[136:139], v[200:203], 0
	v_mfma_f32_16x16x32_bf16 v[124:127], v[132:135], v[180:183], v[124:127]
	v_mfma_f32_16x16x32_bf16 v[120:123], v[140:143], v[180:183], v[120:123]
	v_mfma_f32_16x16x32_bf16 v[108:111], v[132:135], v[188:191], v[108:111]
	v_mfma_f32_16x16x32_bf16 v[104:107], v[140:143], v[188:191], v[104:107]
	v_mfma_f32_16x16x32_bf16 v[92:95], v[132:135], v[196:199], v[92:95]
	v_mfma_f32_16x16x32_bf16 v[88:91], v[140:143], v[196:199], v[88:91]
	v_mfma_f32_16x16x32_bf16 v[76:79], v[132:135], v[204:207], v[76:79]
	v_mfma_f32_16x16x32_bf16 v[72:75], v[140:143], v[204:207], v[72:75]
	v_mfma_f32_16x16x32_bf16 v[116:119], v[156:159], v[176:179], 0
	v_mfma_f32_16x16x32_bf16 v[112:115], v[168:171], v[176:179], 0
	v_mfma_f32_16x16x32_bf16 v[100:103], v[156:159], v[184:187], 0
	v_mfma_f32_16x16x32_bf16 v[96:99], v[168:171], v[184:187], 0
	v_mfma_f32_16x16x32_bf16 v[84:87], v[156:159], v[192:195], 0
	v_mfma_f32_16x16x32_bf16 v[80:83], v[168:171], v[192:195], 0
	v_mfma_f32_16x16x32_bf16 v[68:71], v[156:159], v[200:203], 0
	v_mfma_f32_16x16x32_bf16 v[64:67], v[168:171], v[200:203], 0
	v_mfma_f32_16x16x32_bf16 v[116:119], v[164:167], v[180:183], v[116:119]
	v_mfma_f32_16x16x32_bf16 v[112:115], v[172:175], v[180:183], v[112:115]
	v_mfma_f32_16x16x32_bf16 v[100:103], v[164:167], v[188:191], v[100:103]
	v_mfma_f32_16x16x32_bf16 v[96:99], v[172:175], v[188:191], v[96:99]
	v_mfma_f32_16x16x32_bf16 v[84:87], v[164:167], v[196:199], v[84:87]
	v_mfma_f32_16x16x32_bf16 v[80:83], v[172:175], v[196:199], v[80:83]
	v_mfma_f32_16x16x32_bf16 v[68:71], v[164:167], v[204:207], v[68:71]
	v_mfma_f32_16x16x32_bf16 v[64:67], v[172:175], v[204:207], v[64:67]
	s_barrier
	s_add_i32 m0, s30, 0x10000
	ds_read_b128 v[176:179], v163 offset:16384
	ds_read_b128 v[180:183], v163 offset:17408
	ds_read_b128 v[184:187], v163 offset:18432
	ds_read_b128 v[188:191], v163 offset:19456
	ds_read_b128 v[192:195], v163 offset:20480
	ds_read_b128 v[196:199], v163 offset:21504
	ds_read_b128 v[200:203], v163 offset:22528
	ds_read_b128 v[204:207], v163 offset:23552
	global_load_lds_dwordx4 v148, s[62:63]
	s_add_i32 m0, s30, 0x12000
	s_add_u32 s70, s62, 0x4000
	s_addc_u32 s71, s63, 0
	global_load_lds_dwordx4 v144, s[62:63]
	s_add_i32 m0, s30, 0x14000
	s_add_u32 s18, s18, 0x10000
	s_addc_u32 s19, s19, 0
	global_load_lds_dwordx4 v148, s[70:71]
	s_add_i32 m0, s30, 0x16000
	s_add_u32 s66, s66, 0x10000
	s_addc_u32 s67, s67, 0
	global_load_lds_dwordx4 v144, s[70:71]
	s_mov_b32 m0, s37
	s_nop 0
	global_load_lds_dwordx4 v150, s[64:65]
	s_mov_b32 m0, s39
	s_nop 0
	global_load_lds_dwordx4 v146, s[64:65]
	s_waitcnt vmcnt(8) lgkmcnt(0)
	s_barrier
; #define PG8_STAGE(bufoff, gbase, voff) do { _Pragma("unroll") for (int _i = 0; _i < 2; ++_i) \
;         __builtin_amdgcn_global_load_lds((const unsigned*)((const char*)(gbase) + (voff)[_i]), (PG8_LAS unsigned*)(lds + (bufoff) + ldsw + _i * 8192), 16, 0, 0); } while (0)
; #define PG8_LDA(dst, b, h) do { _Pragma("unroll") for (int m = 0; m < 4; ++m) _Pragma("unroll") for (int k = 0; k < 2; ++k) dst[m][k] = *(const PG8_LAS bf16x8*)(lds + PG8_SA(b, h) + aoff + m * 2048 + k * 1024); } while (0)
; #define PG8_LDB(dst, b, h) do { _Pragma("unroll") for (int n = 0; n < 2; ++n) _Pragma("unroll") for (int k = 0; k < 2; ++k) dst[n][k] = *(const PG8_LAS bf16x8*)(lds + PG8_SB(b, h) + boff + n * 2048 + k * 1024); } while (0)
; template <class Epi, class Sched, bool ALIGN_EPI = false, bool SP2 = false>
; __device__ __forceinline__ void gemm_phase(PG8_LAS unsigned char* lds, const Gemm g, const Sched& S, const Epi& E) {
;     ...
;         for (int t = 0; t < nt; t += 2) {
;             const bool last = (t == nt - 2);
;             const char* a1 = cA + (size_t)(t + 1) * kstep;
;             const char* a2 = last ? nA : cA + (size_t)(t + 2) * kstep; const char* b2 = last ? nB : cB + (size_t)(t + 2) * kstep;
;             const char* a3 = a2 + kstep; const char* b3 = b2 + kstep;
;             if (last && has_next) S.a_ready(nxt);
;             if constexpr (SP2) {
;             PG8_LDB(B0, 0, 0); PG8_LDB(B1, 0, 1); PG8_SCHED; PG8_LDA(At, 0, 0); PG8_STAGE(PG8_SA(1, 1), a1 + hstep, voffA);
;             PG8_WAIT_V(8); PG8_WAIT_L(0); PG8_BAR; PG8_MMA(0, 0, At, B0); PG8_MMA(0, 1, At, B1); PG8_BAR; PG8_SCHED;
;             PG8_LDA(At, 0, 1); PG8_STAGE(PG8_SB(0, 0), b2, voffB); PG8_STAGE(PG8_SB(0, 1), b2 + hstep, voffB); PG8_STAGE(PG8_SA(0, 0), a2, voffA);
;             PG8_WAIT_V(8); PG8_WAIT_L(0); PG8_BAR; PG8_MMA(1, 0, At, B0); PG8_MMA(1, 1, At, B1); PG8_BAR; PG8_SCHED;
;             PG8_LDB(B0, 1, 0); PG8_LDB(B1, 1, 1); PG8_SCHED; PG8_LDA(At, 1, 0); PG8_STAGE(PG8_SA(0, 1), a2 + hstep, voffA);
;             PG8_WAIT_V(8); PG8_WAIT_L(0); PG8_BAR; PG8_MMA(0, 0, At, B0); PG8_MMA(0, 1, At, B1); PG8_BAR; PG8_SCHED;
;             PG8_LDA(At, 1, 1); PG8_STAGE(PG8_SB(1, 0), b3, voffB); PG8_STAGE(PG8_SB(1, 1), b3 + hstep, voffB); PG8_STAGE(PG8_SA(1, 0), a3, voffA);
;             PG8_WAIT_V(8); PG8_WAIT_L(0); PG8_BAR; PG8_MMA(1, 0, At, B0); PG8_MMA(1, 1, At, B1); PG8_BAR; PG8_SCHED;
	v_mfma_f32_16x16x32_bf16 v[60:63], v[128:131], v[176:179], 0
	v_mfma_f32_16x16x32_bf16 v[56:59], v[136:139], v[176:179], 0
	v_mfma_f32_16x16x32_bf16 v[44:47], v[128:131], v[184:187], 0
	v_mfma_f32_16x16x32_bf16 v[40:43], v[136:139], v[184:187], 0
	v_mfma_f32_16x16x32_bf16 v[28:31], v[128:131], v[192:195], 0
	v_mfma_f32_16x16x32_bf16 v[24:27], v[136:139], v[192:195], 0
	v_mfma_f32_16x16x32_bf16 v[12:15], v[128:131], v[200:203], 0
	v_mfma_f32_16x16x32_bf16 v[8:11], v[136:139], v[200:203], 0
	v_mfma_f32_16x16x32_bf16 v[60:63], v[132:135], v[180:183], v[60:63]
	v_mfma_f32_16x16x32_bf16 v[56:59], v[140:143], v[180:183], v[56:59]
	v_mfma_f32_16x16x32_bf16 v[44:47], v[132:135], v[188:191], v[44:47]
	v_mfma_f32_16x16x32_bf16 v[40:43], v[140:143], v[188:191], v[40:43]
	v_mfma_f32_16x16x32_bf16 v[28:31], v[132:135], v[196:199], v[28:31]
	v_mfma_f32_16x16x32_bf16 v[24:27], v[140:143], v[196:199], v[24:27]
	v_mfma_f32_16x16x32_bf16 v[12:15], v[132:135], v[204:207], v[12:15]
	v_mfma_f32_16x16x32_bf16 v[8:11], v[140:143], v[204:207], v[8:11]
	v_mfma_f32_16x16x32_bf16 v[52:55], v[156:159], v[176:179], 0
	v_mfma_f32_16x16x32_bf16 v[48:51], v[168:171], v[176:179], 0
	v_mfma_f32_16x16x32_bf16 v[36:39], v[156:159], v[184:187], 0
	v_mfma_f32_16x16x32_bf16 v[32:35], v[168:171], v[184:187], 0
	v_mfma_f32_16x16x32_bf16 v[20:23], v[156:159], v[192:195], 0
	v_mfma_f32_16x16x32_bf16 v[16:19], v[168:171], v[192:195], 0
	v_mfma_f32_16x16x32_bf16 v[4:7], v[156:159], v[200:203], 0
	v_mfma_f32_16x16x32_bf16 v[0:3], v[168:171], v[200:203], 0
	v_mfma_f32_16x16x32_bf16 v[52:55], v[164:167], v[180:183], v[52:55]
	v_mfma_f32_16x16x32_bf16 v[48:51], v[172:175], v[180:183], v[48:51]
	v_mfma_f32_16x16x32_bf16 v[36:39], v[164:167], v[188:191], v[36:39]
	v_mfma_f32_16x16x32_bf16 v[32:35], v[172:175], v[188:191], v[32:35]
	v_mfma_f32_16x16x32_bf16 v[20:23], v[164:167], v[196:199], v[20:23]
	v_mfma_f32_16x16x32_bf16 v[16:19], v[172:175], v[196:199], v[16:19]
	v_mfma_f32_16x16x32_bf16 v[4:7], v[164:167], v[204:207], v[4:7]
	v_mfma_f32_16x16x32_bf16 v[0:3], v[172:175], v[204:207], v[0:3]
	s_barrier
	ds_read_b128 v[128:131], v254 offset:32768
	ds_read_b128 v[132:135], v254 offset:33792
	ds_read_b128 v[136:139], v254 offset:34816
	ds_read_b128 v[140:143], v254 offset:35840
	ds_read_b128 v[156:159], v254 offset:49152
	ds_read_b128 v[164:167], v254 offset:50176
	ds_read_b128 v[168:171], v254 offset:51200
	ds_read_b128 v[172:175], v254 offset:52224
	s_add_u32 s64, s64, 0x4000
	s_addc_u32 s65, s65, 0
	s_mov_b32 m0, s41
	ds_read_b128 v[176:179], v163 offset:32768
	ds_read_b128 v[180:183], v163 offset:33792
	ds_read_b128 v[184:187], v163 offset:34816
	ds_read_b128 v[188:191], v163 offset:35840
	ds_read_b128 v[192:195], v163 offset:36864
	ds_read_b128 v[196:199], v163 offset:37888
	ds_read_b128 v[200:203], v163 offset:38912
	ds_read_b128 v[204:207], v163 offset:39936
	global_load_lds_dwordx4 v150, s[64:65]
	s_mov_b32 m0, s42
	s_nop 0
	global_load_lds_dwordx4 v146, s[64:65]
	s_waitcnt vmcnt(8) lgkmcnt(0)
	s_barrier
	v_mfma_f32_16x16x32_bf16 v[124:127], v[128:131], v[176:179], v[124:127]
	v_mfma_f32_16x16x32_bf16 v[120:123], v[136:139], v[176:179], v[120:123]
	v_mfma_f32_16x16x32_bf16 v[108:111], v[128:131], v[184:187], v[108:111]
	v_mfma_f32_16x16x32_bf16 v[104:107], v[136:139], v[184:187], v[104:107]
	v_mfma_f32_16x16x32_bf16 v[92:95], v[128:131], v[192:195], v[92:95]
	v_mfma_f32_16x16x32_bf16 v[88:91], v[136:139], v[192:195], v[88:91]
	v_mfma_f32_16x16x32_bf16 v[76:79], v[128:131], v[200:203], v[76:79]
	v_mfma_f32_16x16x32_bf16 v[72:75], v[136:139], v[200:203], v[72:75]
	v_mfma_f32_16x16x32_bf16 v[124:127], v[132:135], v[180:183], v[124:127]
	v_mfma_f32_16x16x32_bf16 v[120:123], v[140:143], v[180:183], v[120:123]
	v_mfma_f32_16x16x32_bf16 v[108:111], v[132:135], v[188:191], v[108:111]
	v_mfma_f32_16x16x32_bf16 v[104:107], v[140:143], v[188:191], v[104:107]
	v_mfma_f32_16x16x32_bf16 v[92:95], v[132:135], v[196:199], v[92:95]
	v_mfma_f32_16x16x32_bf16 v[88:91], v[140:143], v[196:199], v[88:91]
	v_mfma_f32_16x16x32_bf16 v[76:79], v[132:135], v[204:207], v[76:79]
	v_mfma_f32_16x16x32_bf16 v[72:75], v[140:143], v[204:207], v[72:75]
	v_mfma_f32_16x16x32_bf16 v[116:119], v[156:159], v[176:179], v[116:119]
	v_mfma_f32_16x16x32_bf16 v[112:115], v[168:171], v[176:179], v[112:115]
	v_mfma_f32_16x16x32_bf16 v[100:103], v[156:159], v[184:187], v[100:103]
	v_mfma_f32_16x16x32_bf16 v[96:99], v[168:171], v[184:187], v[96:99]
	v_mfma_f32_16x16x32_bf16 v[84:87], v[156:159], v[192:195], v[84:87]
	v_mfma_f32_16x16x32_bf16 v[80:83], v[168:171], v[192:195], v[80:83]
	v_mfma_f32_16x16x32_bf16 v[68:71], v[156:159], v[200:203], v[68:71]
	v_mfma_f32_16x16x32_bf16 v[64:67], v[168:171], v[200:203], v[64:67]
	v_mfma_f32_16x16x32_bf16 v[116:119], v[164:167], v[180:183], v[116:119]
	v_mfma_f32_16x16x32_bf16 v[112:115], v[172:175], v[180:183], v[112:115]
	v_mfma_f32_16x16x32_bf16 v[100:103], v[164:167], v[188:191], v[100:103]
	v_mfma_f32_16x16x32_bf16 v[96:99], v[172:175], v[188:191], v[96:99]
	v_mfma_f32_16x16x32_bf16 v[84:87], v[164:167], v[196:199], v[84:87]
	v_mfma_f32_16x16x32_bf16 v[80:83], v[172:175], v[196:199], v[80:83]
	v_mfma_f32_16x16x32_bf16 v[68:71], v[164:167], v[204:207], v[68:71]
	v_mfma_f32_16x16x32_bf16 v[64:67], v[172:175], v[204:207], v[64:67]
	s_barrier
; #define PG8_STAGE(bufoff, gbase, voff) do { _Pragma("unroll") for (int _i = 0; _i < 2; ++_i) \
;         __builtin_amdgcn_global_load_lds((const unsigned*)((const char*)(gbase) + (voff)[_i]), (PG8_LAS unsigned*)(lds + (bufoff) + ldsw + _i * 8192), 16, 0, 0); } while (0)
; #define PG8_LDA(dst, b, h) do { _Pragma("unroll") for (int m = 0; m < 4; ++m) _Pragma("unroll") for (int k = 0; k < 2; ++k) dst[m][k] = *(const PG8_LAS bf16x8*)(lds + PG8_SA(b, h) + aoff + m * 2048 + k * 1024); } while (0)
; #define PG8_LDB(dst, b, h) do { _Pragma("unroll") for (int n = 0; n < 2; ++n) _Pragma("unroll") for (int k = 0; k < 2; ++k) dst[n][k] = *(const PG8_LAS bf16x8*)(lds + PG8_SB(b, h) + boff + n * 2048 + k * 1024); } while (0)
; template <class Epi, class Sched, bool ALIGN_EPI = false, bool SP2 = false>
; __device__ __forceinline__ void gemm_phase(PG8_LAS unsigned char* lds, const Gemm g, const Sched& S, const Epi& E) {
;     ...
;         for (int t = 0; t < nt; t += 2) {
;             const bool last = (t == nt - 2);
;             const char* a1 = cA + (size_t)(t + 1) * kstep;
;             const char* a2 = last ? nA : cA + (size_t)(t + 2) * kstep; const char* b2 = last ? nB : cB + (size_t)(t + 2) * kstep;
;             const char* a3 = a2 + kstep; const char* b3 = b2 + kstep;
;             if (last && has_next) S.a_ready(nxt);
;             if constexpr (SP2) {
;             PG8_LDB(B0, 0, 0); PG8_LDB(B1, 0, 1); PG8_SCHED; PG8_LDA(At, 0, 0); PG8_STAGE(PG8_SA(1, 1), a1 + hstep, voffA);
;             PG8_WAIT_V(8); PG8_WAIT_L(0); PG8_BAR; PG8_MMA(0, 0, At, B0); PG8_MMA(0, 1, At, B1); PG8_BAR; PG8_SCHED;
;             PG8_LDA(At, 0, 1); PG8_STAGE(PG8_SB(0, 0), b2, voffB); PG8_STAGE(PG8_SB(0, 1), b2 + hstep, voffB); PG8_STAGE(PG8_SA(0, 0), a2, voffA);
;             PG8_WAIT_V(8); PG8_WAIT_L(0); PG8_BAR; PG8_MMA(1, 0, At, B0); PG8_MMA(1, 1, At, B1); PG8_BAR; PG8_SCHED;
;             PG8_LDB(B0, 1, 0); PG8_LDB(B1, 1, 1); PG8_SCHED; PG8_LDA(At, 1, 0); PG8_STAGE(PG8_SA(0, 1), a2 + hstep, voffA);
;             PG8_WAIT_V(8); PG8_WAIT_L(0); PG8_BAR; PG8_MMA(0, 0, At, B0); PG8_MMA(0, 1, At, B1); PG8_BAR; PG8_SCHED;
;             PG8_LDA(At, 1, 1); PG8_STAGE(PG8_SB(1, 0), b3, voffB); PG8_STAGE(PG8_SB(1, 1), b3 + hstep, voffB); PG8_STAGE(PG8_SA(1, 0), a3, voffA);
;             PG8_WAIT_V(8); PG8_WAIT_L(0); PG8_BAR; PG8_MMA(1, 0, At, B0); PG8_MMA(1, 1, At, B1); PG8_BAR; PG8_SCHED;
	s_add_u32 s64, s62, 0x8000
	s_addc_u32 s65, s63, 0
	s_add_i32 m0, s30, 0x18000
	ds_read_b128 v[176:179], v163 offset:49152
	ds_read_b128 v[180:183], v163 offset:50176
	ds_read_b128 v[184:187], v163 offset:51200
	ds_read_b128 v[188:191], v163 offset:52224
	ds_read_b128 v[192:195], v163 offset:53248
	ds_read_b128 v[196:199], v163 offset:54272
	ds_read_b128 v[200:203], v163 offset:55296
	ds_read_b128 v[204:207], v163 offset:56320
	global_load_lds_dwordx4 v148, s[64:65]
	s_add_i32 m0, s30, 0x1a000
	s_add_u32 s62, s62, 0xc000
	s_addc_u32 s63, s63, 0
	global_load_lds_dwordx4 v144, s[64:65]
	s_add_i32 m0, s30, 0x1c000
	s_nop 0
	global_load_lds_dwordx4 v148, s[62:63]
	s_add_i32 m0, s30, 0x1e000
	s_nop 0
	global_load_lds_dwordx4 v144, s[62:63]
	s_mov_b32 m0, s54
	s_nop 0
	global_load_lds_dwordx4 v150, s[20:21]
	s_mov_b32 m0, s55
	s_nop 0
	global_load_lds_dwordx4 v146, s[20:21]
	s_waitcnt vmcnt(8) lgkmcnt(0)
	s_barrier
	v_mfma_f32_16x16x32_bf16 v[60:63], v[128:131], v[176:179], v[60:63]
	v_mfma_f32_16x16x32_bf16 v[56:59], v[136:139], v[176:179], v[56:59]
	v_mfma_f32_16x16x32_bf16 v[44:47], v[128:131], v[184:187], v[44:47]
	v_mfma_f32_16x16x32_bf16 v[40:43], v[136:139], v[184:187], v[40:43]
	v_mfma_f32_16x16x32_bf16 v[28:31], v[128:131], v[192:195], v[28:31]
	v_mfma_f32_16x16x32_bf16 v[24:27], v[136:139], v[192:195], v[24:27]
	v_mfma_f32_16x16x32_bf16 v[12:15], v[128:131], v[200:203], v[12:15]
	v_mfma_f32_16x16x32_bf16 v[8:11], v[136:139], v[200:203], v[8:11]
	v_mfma_f32_16x16x32_bf16 v[60:63], v[132:135], v[180:183], v[60:63]
	v_mfma_f32_16x16x32_bf16 v[56:59], v[140:143], v[180:183], v[56:59]
	v_mfma_f32_16x16x32_bf16 v[44:47], v[132:135], v[188:191], v[44:47]
	v_mfma_f32_16x16x32_bf16 v[40:43], v[140:143], v[188:191], v[40:43]
	v_mfma_f32_16x16x32_bf16 v[28:31], v[132:135], v[196:199], v[28:31]
	v_mfma_f32_16x16x32_bf16 v[24:27], v[140:143], v[196:199], v[24:27]
	v_mfma_f32_16x16x32_bf16 v[12:15], v[132:135], v[204:207], v[12:15]
	v_mfma_f32_16x16x32_bf16 v[8:11], v[140:143], v[204:207], v[8:11]
	v_mfma_f32_16x16x32_bf16 v[52:55], v[156:159], v[176:179], v[52:55]
	v_mfma_f32_16x16x32_bf16 v[48:51], v[168:171], v[176:179], v[48:51]
	v_mfma_f32_16x16x32_bf16 v[36:39], v[156:159], v[184:187], v[36:39]
	v_mfma_f32_16x16x32_bf16 v[32:35], v[168:171], v[184:187], v[32:35]
	v_mfma_f32_16x16x32_bf16 v[20:23], v[156:159], v[192:195], v[20:23]
	v_mfma_f32_16x16x32_bf16 v[16:19], v[168:171], v[192:195], v[16:19]
	v_mfma_f32_16x16x32_bf16 v[4:7], v[156:159], v[200:203], v[4:7]
	v_mfma_f32_16x16x32_bf16 v[0:3], v[168:171], v[200:203], v[0:3]
	v_mfma_f32_16x16x32_bf16 v[52:55], v[164:167], v[180:183], v[52:55]
	v_mfma_f32_16x16x32_bf16 v[48:51], v[172:175], v[180:183], v[48:51]
	v_mfma_f32_16x16x32_bf16 v[36:39], v[164:167], v[188:191], v[36:39]
	v_mfma_f32_16x16x32_bf16 v[32:35], v[172:175], v[188:191], v[32:35]
	v_mfma_f32_16x16x32_bf16 v[20:23], v[164:167], v[196:199], v[20:23]
	v_mfma_f32_16x16x32_bf16 v[16:19], v[172:175], v[196:199], v[16:19]
	v_mfma_f32_16x16x32_bf16 v[4:7], v[164:167], v[204:207], v[4:7]
	v_mfma_f32_16x16x32_bf16 v[0:3], v[172:175], v[204:207], v[0:3]
	s_barrier
	s_add_i32 s68, s68, 2
	s_cmp_gt_u32 s68, 13
.LBB0_1356:
	s_add_u32 s20, s18, 0x4000
	s_addc_u32 s21, s19, 0
	s_cmp_eq_u32 s68, 12
	s_cselect_b32 s64, s40, s20
	s_cselect_b32 s65, s11, s21
	s_cselect_b32 s62, s61, s66
	s_cselect_b32 s63, s9, s67
	ds_read_b128 v[128:131], v254
	ds_read_b128 v[132:135], v254 offset:1024
	ds_read_b128 v[136:139], v254 offset:2048
	ds_read_b128 v[140:143], v254 offset:3072
	ds_read_b128 v[156:159], v254 offset:16384
	ds_read_b128 v[164:167], v254 offset:17408
	ds_read_b128 v[168:171], v254 offset:18432
	ds_read_b128 v[172:175], v254 offset:19456
	s_add_i32 m0, s37, 0xc000
	ds_read_b128 v[176:179], v163
	ds_read_b128 v[180:183], v163 offset:1024
	ds_read_b128 v[184:187], v163 offset:2048
	ds_read_b128 v[188:191], v163 offset:3072
	ds_read_b128 v[192:195], v163 offset:4096
	ds_read_b128 v[196:199], v163 offset:5120
	ds_read_b128 v[200:203], v163 offset:6144
	ds_read_b128 v[204:207], v163 offset:7168
	global_load_lds_dwordx4 v152, s[18:19]
	s_add_i32 m0, s37, 0xe000
	s_add_u32 s20, s64, 0x8000
	s_addc_u32 s21, s65, 0
	global_load_lds_dwordx4 v154, s[18:19]
	s_waitcnt vmcnt(8) lgkmcnt(0)
	s_barrier
	v_mfma_f32_16x16x32_bf16 v[124:127], v[128:131], v[176:179], v[124:127]
	v_mfma_f32_16x16x32_bf16 v[120:123], v[136:139], v[176:179], v[120:123]
	v_mfma_f32_16x16x32_bf16 v[108:111], v[128:131], v[184:187], v[108:111]
	v_mfma_f32_16x16x32_bf16 v[104:107], v[136:139], v[184:187], v[104:107]
	v_mfma_f32_16x16x32_bf16 v[92:95], v[128:131], v[192:195], v[92:95]
	v_mfma_f32_16x16x32_bf16 v[88:91], v[136:139], v[192:195], v[88:91]
	v_mfma_f32_16x16x32_bf16 v[76:79], v[128:131], v[200:203], v[76:79]
	v_mfma_f32_16x16x32_bf16 v[72:75], v[136:139], v[200:203], v[72:75]
	v_mfma_f32_16x16x32_bf16 v[124:127], v[132:135], v[180:183], v[124:127]
	v_mfma_f32_16x16x32_bf16 v[120:123], v[140:143], v[180:183], v[120:123]
	v_mfma_f32_16x16x32_bf16 v[108:111], v[132:135], v[188:191], v[108:111]
	v_mfma_f32_16x16x32_bf16 v[104:107], v[140:143], v[188:191], v[104:107]
	v_mfma_f32_16x16x32_bf16 v[92:95], v[132:135], v[196:199], v[92:95]
	v_mfma_f32_16x16x32_bf16 v[88:91], v[140:143], v[196:199], v[88:91]
	v_mfma_f32_16x16x32_bf16 v[76:79], v[132:135], v[204:207], v[76:79]
	v_mfma_f32_16x16x32_bf16 v[72:75], v[140:143], v[204:207], v[72:75]
	v_mfma_f32_16x16x32_bf16 v[116:119], v[156:159], v[176:179], v[116:119]
	v_mfma_f32_16x16x32_bf16 v[112:115], v[168:171], v[176:179], v[112:115]
	v_mfma_f32_16x16x32_bf16 v[100:103], v[156:159], v[184:187], v[100:103]
	v_mfma_f32_16x16x32_bf16 v[96:99], v[168:171], v[184:187], v[96:99]
	v_mfma_f32_16x16x32_bf16 v[84:87], v[156:159], v[192:195], v[84:87]
	v_mfma_f32_16x16x32_bf16 v[80:83], v[168:171], v[192:195], v[80:83]
	v_mfma_f32_16x16x32_bf16 v[68:71], v[156:159], v[200:203], v[68:71]
	v_mfma_f32_16x16x32_bf16 v[64:67], v[168:171], v[200:203], v[64:67]
	v_mfma_f32_16x16x32_bf16 v[116:119], v[164:167], v[180:183], v[116:119]
	v_mfma_f32_16x16x32_bf16 v[112:115], v[172:175], v[180:183], v[112:115]
	v_mfma_f32_16x16x32_bf16 v[100:103], v[164:167], v[188:191], v[100:103]
	v_mfma_f32_16x16x32_bf16 v[96:99], v[172:175], v[188:191], v[96:99]
	v_mfma_f32_16x16x32_bf16 v[84:87], v[164:167], v[196:199], v[84:87]
	v_mfma_f32_16x16x32_bf16 v[80:83], v[172:175], v[196:199], v[80:83]
	v_mfma_f32_16x16x32_bf16 v[68:71], v[164:167], v[204:207], v[68:71]
	v_mfma_f32_16x16x32_bf16 v[64:67], v[172:175], v[204:207], v[64:67]
	s_barrier
; #define PG8_STAGE(bufoff, gbase, voff) do { _Pragma("unroll") for (int _i = 0; _i < 2; ++_i) \
;         __builtin_amdgcn_global_load_lds((const unsigned*)((const char*)(gbase) + (voff)[_i]), (PG8_LAS unsigned*)(lds + (bufoff) + ldsw + _i * 8192), 16, 0, 0); } while (0)
; #define PG8_LDA(dst, b, h) do { _Pragma("unroll") for (int m = 0; m < 4; ++m) _Pragma("unroll") for (int k = 0; k < 2; ++k) dst[m][k] = *(const PG8_LAS bf16x8*)(lds + PG8_SA(b, h) + aoff + m * 2048 + k * 1024); } while (0)
; #define PG8_LDB(dst, b, h) do { _Pragma("unroll") for (int n = 0; n < 2; ++n) _Pragma("unroll") for (int k = 0; k < 2; ++k) dst[n][k] = *(const PG8_LAS bf16x8*)(lds + PG8_SB(b, h) + boff + n * 2048 + k * 1024); } while (0)
; #define PG8_MMA(ai, bj, At, Bt) do { __builtin_amdgcn_s_setprio(1); _Pragma("unroll") for (int m = 0; m < 4; ++m) _Pragma("unroll") for (int n = 0; n < 2; ++n) _Pragma("unroll") for (int k = 0; k < 2; ++k) \
;         acc[ai][bj][m][n] = __builtin_amdgcn_mfma_f32_16x16x32_bf16(Bt[n][k], At[m][k], acc[ai][bj][m][n], 0, 0, 0); __builtin_amdgcn_s_setprio(0); } while (0)
; #define PG8_WAIT_V(n) asm volatile("s_waitcnt vmcnt(" #n ")" ::: "memory")
; template <class Epi, class Sched, bool ALIGN_EPI = false, bool SP2 = false>
; __device__ __forceinline__ void gemm_phase(PG8_LAS unsigned char* lds, const Gemm g, const Sched& S, const Epi& E) {
;     ...
;             PG8_LDB(B0, 0, 0); PG8_LDB(B1, 0, 1); PG8_SCHED; PG8_LDA(At, 0, 0); PG8_STAGE(PG8_SA(1, 1), a1 + hstep, voffA);
;             PG8_WAIT_V(8); PG8_WAIT_L(0); PG8_BAR; PG8_MMA(0, 0, At, B0); PG8_MMA(0, 1, At, B1); PG8_BAR; PG8_SCHED;
;             PG8_LDA(At, 0, 1); PG8_STAGE(PG8_SB(0, 0), b2, voffB); PG8_STAGE(PG8_SB(0, 1), b2 + hstep, voffB); PG8_STAGE(PG8_SA(0, 0), a2, voffA);
;             PG8_WAIT_V(8); PG8_WAIT_L(0); PG8_BAR; PG8_MMA(1, 0, At, B0); PG8_MMA(1, 1, At, B1); PG8_BAR; PG8_SCHED;
;             PG8_LDB(B0, 1, 0); PG8_LDB(B1, 1, 1); PG8_SCHED; PG8_LDA(At, 1, 0); PG8_STAGE(PG8_SA(0, 1), a2 + hstep, voffA);
;             PG8_WAIT_V(8); PG8_WAIT_L(0); PG8_BAR; PG8_MMA(0, 0, At, B0); PG8_MMA(0, 1, At, B1); PG8_BAR; PG8_SCHED;
;             PG8_LDA(At, 1, 1); PG8_STAGE(PG8_SB(1, 0), b3, voffB); PG8_STAGE(PG8_SB(1, 1), b3 + hstep, voffB); PG8_STAGE(PG8_SA(1, 0), a3, voffA);
;             PG8_WAIT_V(8); PG8_WAIT_L(0); PG8_BAR; PG8_MMA(1, 0, At, B0); PG8_MMA(1, 1, At, B1); PG8_BAR; PG8_SCHED;
	s_add_i32 m0, s30, 0x10000
	ds_read_b128 v[176:179], v163 offset:16384
	ds_read_b128 v[180:183], v163 offset:17408
	ds_read_b128 v[184:187], v163 offset:18432
	ds_read_b128 v[188:191], v163 offset:19456
	ds_read_b128 v[192:195], v163 offset:20480
	ds_read_b128 v[196:199], v163 offset:21504
	ds_read_b128 v[200:203], v163 offset:22528
	ds_read_b128 v[204:207], v163 offset:23552
	global_load_lds_dwordx4 v148, s[62:63]
	s_add_i32 m0, s30, 0x12000
	s_add_u32 s70, s62, 0x4000
	s_addc_u32 s71, s63, 0
	global_load_lds_dwordx4 v144, s[62:63]
	s_add_i32 m0, s30, 0x14000
	s_add_u32 s18, s18, 0x10000
	s_addc_u32 s19, s19, 0
	global_load_lds_dwordx4 v148, s[70:71]
	s_add_i32 m0, s30, 0x16000
	s_add_u32 s66, s66, 0x10000
	s_addc_u32 s67, s67, 0
	global_load_lds_dwordx4 v144, s[70:71]
	s_mov_b32 m0, s37
	s_nop 0
	global_load_lds_dwordx4 v150, s[64:65]
	s_mov_b32 m0, s39
	s_nop 0
	global_load_lds_dwordx4 v146, s[64:65]
	s_waitcnt vmcnt(8) lgkmcnt(0)
	s_barrier
	v_mfma_f32_16x16x32_bf16 v[60:63], v[128:131], v[176:179], v[60:63]
	v_mfma_f32_16x16x32_bf16 v[56:59], v[136:139], v[176:179], v[56:59]
	v_mfma_f32_16x16x32_bf16 v[44:47], v[128:131], v[184:187], v[44:47]
	v_mfma_f32_16x16x32_bf16 v[40:43], v[136:139], v[184:187], v[40:43]
	v_mfma_f32_16x16x32_bf16 v[28:31], v[128:131], v[192:195], v[28:31]
	v_mfma_f32_16x16x32_bf16 v[24:27], v[136:139], v[192:195], v[24:27]
	v_mfma_f32_16x16x32_bf16 v[12:15], v[128:131], v[200:203], v[12:15]
	v_mfma_f32_16x16x32_bf16 v[8:11], v[136:139], v[200:203], v[8:11]
	v_mfma_f32_16x16x32_bf16 v[60:63], v[132:135], v[180:183], v[60:63]
	v_mfma_f32_16x16x32_bf16 v[56:59], v[140:143], v[180:183], v[56:59]
	v_mfma_f32_16x16x32_bf16 v[44:47], v[132:135], v[188:191], v[44:47]
	v_mfma_f32_16x16x32_bf16 v[40:43], v[140:143], v[188:191], v[40:43]
	v_mfma_f32_16x16x32_bf16 v[28:31], v[132:135], v[196:199], v[28:31]
	v_mfma_f32_16x16x32_bf16 v[24:27], v[140:143], v[196:199], v[24:27]
	v_mfma_f32_16x16x32_bf16 v[12:15], v[132:135], v[204:207], v[12:15]
	v_mfma_f32_16x16x32_bf16 v[8:11], v[140:143], v[204:207], v[8:11]
	v_mfma_f32_16x16x32_bf16 v[52:55], v[156:159], v[176:179], v[52:55]
	v_mfma_f32_16x16x32_bf16 v[48:51], v[168:171], v[176:179], v[48:51]
	v_mfma_f32_16x16x32_bf16 v[36:39], v[156:159], v[184:187], v[36:39]
	v_mfma_f32_16x16x32_bf16 v[32:35], v[168:171], v[184:187], v[32:35]
	v_mfma_f32_16x16x32_bf16 v[20:23], v[156:159], v[192:195], v[20:23]
	v_mfma_f32_16x16x32_bf16 v[16:19], v[168:171], v[192:195], v[16:19]
	v_mfma_f32_16x16x32_bf16 v[4:7], v[156:159], v[200:203], v[4:7]
	v_mfma_f32_16x16x32_bf16 v[0:3], v[168:171], v[200:203], v[0:3]
	v_mfma_f32_16x16x32_bf16 v[52:55], v[164:167], v[180:183], v[52:55]
	v_mfma_f32_16x16x32_bf16 v[48:51], v[172:175], v[180:183], v[48:51]
	v_mfma_f32_16x16x32_bf16 v[36:39], v[164:167], v[188:191], v[36:39]
	v_mfma_f32_16x16x32_bf16 v[32:35], v[172:175], v[188:191], v[32:35]
	v_mfma_f32_16x16x32_bf16 v[20:23], v[164:167], v[196:199], v[20:23]
	v_mfma_f32_16x16x32_bf16 v[16:19], v[172:175], v[196:199], v[16:19]
	v_mfma_f32_16x16x32_bf16 v[4:7], v[164:167], v[204:207], v[4:7]
	v_mfma_f32_16x16x32_bf16 v[0:3], v[172:175], v[204:207], v[0:3]
	s_barrier
	ds_read_b128 v[128:131], v254 offset:32768
	ds_read_b128 v[132:135], v254 offset:33792
	ds_read_b128 v[136:139], v254 offset:34816
	ds_read_b128 v[140:143], v254 offset:35840
	ds_read_b128 v[156:159], v254 offset:49152
	ds_read_b128 v[164:167], v254 offset:50176
	ds_read_b128 v[168:171], v254 offset:51200
	ds_read_b128 v[172:175], v254 offset:52224
	s_add_u32 s64, s64, 0x4000
	s_addc_u32 s65, s65, 0
	s_mov_b32 m0, s41
	ds_read_b128 v[176:179], v163 offset:32768
	ds_read_b128 v[180:183], v163 offset:33792
	ds_read_b128 v[184:187], v163 offset:34816
	ds_read_b128 v[188:191], v163 offset:35840
	ds_read_b128 v[192:195], v163 offset:36864
	ds_read_b128 v[196:199], v163 offset:37888
	ds_read_b128 v[200:203], v163 offset:38912
	ds_read_b128 v[204:207], v163 offset:39936
	global_load_lds_dwordx4 v150, s[64:65]
	s_mov_b32 m0, s42
	s_nop 0
	global_load_lds_dwordx4 v146, s[64:65]
	s_waitcnt vmcnt(8) lgkmcnt(0)
	s_barrier
; #define PG8_STAGE(bufoff, gbase, voff) do { _Pragma("unroll") for (int _i = 0; _i < 2; ++_i) \
;         __builtin_amdgcn_global_load_lds((const unsigned*)((const char*)(gbase) + (voff)[_i]), (PG8_LAS unsigned*)(lds + (bufoff) + ldsw + _i * 8192), 16, 0, 0); } while (0)
; #define PG8_LDA(dst, b, h) do { _Pragma("unroll") for (int m = 0; m < 4; ++m) _Pragma("unroll") for (int k = 0; k < 2; ++k) dst[m][k] = *(const PG8_LAS bf16x8*)(lds + PG8_SA(b, h) + aoff + m * 2048 + k * 1024); } while (0)
; #define PG8_LDB(dst, b, h) do { _Pragma("unroll") for (int n = 0; n < 2; ++n) _Pragma("unroll") for (int k = 0; k < 2; ++k) dst[n][k] = *(const PG8_LAS bf16x8*)(lds + PG8_SB(b, h) + boff + n * 2048 + k * 1024); } while (0)
; #define PG8_MMA(ai, bj, At, Bt) do { __builtin_amdgcn_s_setprio(1); _Pragma("unroll") for (int m = 0; m < 4; ++m) _Pragma("unroll") for (int n = 0; n < 2; ++n) _Pragma("unroll") for (int k = 0; k < 2; ++k) \
;         acc[ai][bj][m][n] = __builtin_amdgcn_mfma_f32_16x16x32_bf16(Bt[n][k], At[m][k], acc[ai][bj][m][n], 0, 0, 0); __builtin_amdgcn_s_setprio(0); } while (0)
; template <class Epi, class Sched, bool ALIGN_EPI = false, bool SP2 = false>
; __device__ __forceinline__ void gemm_phase(PG8_LAS unsigned char* lds, const Gemm g, const Sched& S, const Epi& E) {
;     ...
;             PG8_LDB(B0, 0, 0); PG8_LDB(B1, 0, 1); PG8_SCHED; PG8_LDA(At, 0, 0); PG8_STAGE(PG8_SA(1, 1), a1 + hstep, voffA);
;             PG8_WAIT_V(8); PG8_WAIT_L(0); PG8_BAR; PG8_MMA(0, 0, At, B0); PG8_MMA(0, 1, At, B1); PG8_BAR; PG8_SCHED;
;             PG8_LDA(At, 0, 1); PG8_STAGE(PG8_SB(0, 0), b2, voffB); PG8_STAGE(PG8_SB(0, 1), b2 + hstep, voffB); PG8_STAGE(PG8_SA(0, 0), a2, voffA);
;             PG8_WAIT_V(8); PG8_WAIT_L(0); PG8_BAR; PG8_MMA(1, 0, At, B0); PG8_MMA(1, 1, At, B1); PG8_BAR; PG8_SCHED;
;             PG8_LDB(B0, 1, 0); PG8_LDB(B1, 1, 1); PG8_SCHED; PG8_LDA(At, 1, 0); PG8_STAGE(PG8_SA(0, 1), a2 + hstep, voffA);
;             PG8_WAIT_V(8); PG8_WAIT_L(0); PG8_BAR; PG8_MMA(0, 0, At, B0); PG8_MMA(0, 1, At, B1); PG8_BAR; PG8_SCHED;
;             PG8_LDA(At, 1, 1); PG8_STAGE(PG8_SB(1, 0), b3, voffB); PG8_STAGE(PG8_SB(1, 1), b3 + hstep, voffB); PG8_STAGE(PG8_SA(1, 0), a3, voffA);
;             PG8_WAIT_V(8); PG8_WAIT_L(0); PG8_BAR; PG8_MMA(1, 0, At, B0); PG8_MMA(1, 1, At, B1); PG8_BAR; PG8_SCHED;
;     ...
;         if constexpr (ALIGN_EPI) { if (wr == 0) PG8_BAR; }
	v_mfma_f32_16x16x32_bf16 v[124:127], v[128:131], v[176:179], v[124:127]
	v_mfma_f32_16x16x32_bf16 v[120:123], v[136:139], v[176:179], v[120:123]
	v_mfma_f32_16x16x32_bf16 v[108:111], v[128:131], v[184:187], v[108:111]
	v_mfma_f32_16x16x32_bf16 v[104:107], v[136:139], v[184:187], v[104:107]
	v_mfma_f32_16x16x32_bf16 v[92:95], v[128:131], v[192:195], v[92:95]
	v_mfma_f32_16x16x32_bf16 v[88:91], v[136:139], v[192:195], v[88:91]
	v_mfma_f32_16x16x32_bf16 v[76:79], v[128:131], v[200:203], v[76:79]
	v_mfma_f32_16x16x32_bf16 v[72:75], v[136:139], v[200:203], v[72:75]
	v_mfma_f32_16x16x32_bf16 v[124:127], v[132:135], v[180:183], v[124:127]
	v_mfma_f32_16x16x32_bf16 v[120:123], v[140:143], v[180:183], v[120:123]
	v_mfma_f32_16x16x32_bf16 v[108:111], v[132:135], v[188:191], v[108:111]
	v_mfma_f32_16x16x32_bf16 v[104:107], v[140:143], v[188:191], v[104:107]
	v_mfma_f32_16x16x32_bf16 v[92:95], v[132:135], v[196:199], v[92:95]
	v_mfma_f32_16x16x32_bf16 v[88:91], v[140:143], v[196:199], v[88:91]
	v_mfma_f32_16x16x32_bf16 v[76:79], v[132:135], v[204:207], v[76:79]
	v_mfma_f32_16x16x32_bf16 v[72:75], v[140:143], v[204:207], v[72:75]
	v_mfma_f32_16x16x32_bf16 v[116:119], v[156:159], v[176:179], v[116:119]
	v_mfma_f32_16x16x32_bf16 v[112:115], v[168:171], v[176:179], v[112:115]
	v_mfma_f32_16x16x32_bf16 v[100:103], v[156:159], v[184:187], v[100:103]
	v_mfma_f32_16x16x32_bf16 v[96:99], v[168:171], v[184:187], v[96:99]
	v_mfma_f32_16x16x32_bf16 v[84:87], v[156:159], v[192:195], v[84:87]
	v_mfma_f32_16x16x32_bf16 v[80:83], v[168:171], v[192:195], v[80:83]
	v_mfma_f32_16x16x32_bf16 v[68:71], v[156:159], v[200:203], v[68:71]
	v_mfma_f32_16x16x32_bf16 v[64:67], v[168:171], v[200:203], v[64:67]
	v_mfma_f32_16x16x32_bf16 v[116:119], v[164:167], v[180:183], v[116:119]
	v_mfma_f32_16x16x32_bf16 v[112:115], v[172:175], v[180:183], v[112:115]
	v_mfma_f32_16x16x32_bf16 v[100:103], v[164:167], v[188:191], v[100:103]
	v_mfma_f32_16x16x32_bf16 v[96:99], v[172:175], v[188:191], v[96:99]
	v_mfma_f32_16x16x32_bf16 v[84:87], v[164:167], v[196:199], v[84:87]
	v_mfma_f32_16x16x32_bf16 v[80:83], v[172:175], v[196:199], v[80:83]
	v_mfma_f32_16x16x32_bf16 v[68:71], v[164:167], v[204:207], v[68:71]
	v_mfma_f32_16x16x32_bf16 v[64:67], v[172:175], v[204:207], v[64:67]
	s_barrier
	s_add_u32 s64, s62, 0x8000
	s_addc_u32 s65, s63, 0
	s_add_i32 m0, s30, 0x18000
	ds_read_b128 v[176:179], v163 offset:49152
	ds_read_b128 v[180:183], v163 offset:50176
	ds_read_b128 v[184:187], v163 offset:51200
	ds_read_b128 v[188:191], v163 offset:52224
	ds_read_b128 v[192:195], v163 offset:53248
	ds_read_b128 v[196:199], v163 offset:54272
	ds_read_b128 v[200:203], v163 offset:55296
	ds_read_b128 v[204:207], v163 offset:56320
	global_load_lds_dwordx4 v148, s[64:65]
	s_add_i32 m0, s30, 0x1a000
	s_add_u32 s62, s62, 0xc000
	s_addc_u32 s63, s63, 0
	global_load_lds_dwordx4 v144, s[64:65]
	s_add_i32 m0, s30, 0x1c000
	s_nop 0
	global_load_lds_dwordx4 v148, s[62:63]
	s_add_i32 m0, s30, 0x1e000
	s_nop 0
	global_load_lds_dwordx4 v144, s[62:63]
	s_mov_b32 m0, s54
	s_nop 0
	global_load_lds_dwordx4 v150, s[20:21]
	s_mov_b32 m0, s55
	s_nop 0
	global_load_lds_dwordx4 v146, s[20:21]
	s_waitcnt vmcnt(8) lgkmcnt(0)
	s_barrier
	v_mfma_f32_16x16x32_bf16 v[60:63], v[128:131], v[176:179], v[60:63]
	v_mfma_f32_16x16x32_bf16 v[56:59], v[136:139], v[176:179], v[56:59]
	v_mfma_f32_16x16x32_bf16 v[44:47], v[128:131], v[184:187], v[44:47]
	v_mfma_f32_16x16x32_bf16 v[40:43], v[136:139], v[184:187], v[40:43]
	v_mfma_f32_16x16x32_bf16 v[28:31], v[128:131], v[192:195], v[28:31]
	v_mfma_f32_16x16x32_bf16 v[24:27], v[136:139], v[192:195], v[24:27]
	v_mfma_f32_16x16x32_bf16 v[12:15], v[128:131], v[200:203], v[12:15]
	v_mfma_f32_16x16x32_bf16 v[8:11], v[136:139], v[200:203], v[8:11]
	v_mfma_f32_16x16x32_bf16 v[60:63], v[132:135], v[180:183], v[60:63]
	v_mfma_f32_16x16x32_bf16 v[56:59], v[140:143], v[180:183], v[56:59]
	v_mfma_f32_16x16x32_bf16 v[44:47], v[132:135], v[188:191], v[44:47]
	v_mfma_f32_16x16x32_bf16 v[40:43], v[140:143], v[188:191], v[40:43]
	v_mfma_f32_16x16x32_bf16 v[28:31], v[132:135], v[196:199], v[28:31]
	v_mfma_f32_16x16x32_bf16 v[24:27], v[140:143], v[196:199], v[24:27]
	v_mfma_f32_16x16x32_bf16 v[12:15], v[132:135], v[204:207], v[12:15]
	v_mfma_f32_16x16x32_bf16 v[8:11], v[140:143], v[204:207], v[8:11]
	v_mfma_f32_16x16x32_bf16 v[52:55], v[156:159], v[176:179], v[52:55]
	v_mfma_f32_16x16x32_bf16 v[48:51], v[168:171], v[176:179], v[48:51]
	v_mfma_f32_16x16x32_bf16 v[36:39], v[156:159], v[184:187], v[36:39]
	v_mfma_f32_16x16x32_bf16 v[32:35], v[168:171], v[184:187], v[32:35]
	v_mfma_f32_16x16x32_bf16 v[20:23], v[156:159], v[192:195], v[20:23]
	v_mfma_f32_16x16x32_bf16 v[16:19], v[168:171], v[192:195], v[16:19]
	v_mfma_f32_16x16x32_bf16 v[4:7], v[156:159], v[200:203], v[4:7]
	v_mfma_f32_16x16x32_bf16 v[0:3], v[168:171], v[200:203], v[0:3]
	v_mfma_f32_16x16x32_bf16 v[52:55], v[164:167], v[180:183], v[52:55]
	v_mfma_f32_16x16x32_bf16 v[48:51], v[172:175], v[180:183], v[48:51]
	v_mfma_f32_16x16x32_bf16 v[36:39], v[164:167], v[188:191], v[36:39]
	v_mfma_f32_16x16x32_bf16 v[32:35], v[172:175], v[188:191], v[32:35]
	v_mfma_f32_16x16x32_bf16 v[20:23], v[164:167], v[196:199], v[20:23]
	v_mfma_f32_16x16x32_bf16 v[16:19], v[172:175], v[196:199], v[16:19]
	v_mfma_f32_16x16x32_bf16 v[4:7], v[164:167], v[204:207], v[4:7]
	v_mfma_f32_16x16x32_bf16 v[0:3], v[172:175], v[204:207], v[0:3]
	s_barrier
	s_add_i32 s68, s68, 2
	s_cmp_gt_u32 s68, 13
	s_cbranch_scc0 .LBB0_1356
	s_and_b64 vcc, exec, s[6:7]
	s_cbranch_vccz .LBB0_1359
	s_barrier
